# skinny GEMM epilogue (xo, down): residual-row and gain/bias loads hoisted next to the statistics loads, one exposed latency instead of three
# speedup vs baseline: 1.0109x; 1.0020x over previous
; #define LAS __attribute__((address_space(3)))
; template <int KSPLIT, class F>
; __device__ __forceinline__ void skinny_gemm(const bf16_t* A, const bf16_t* Bt, int N, int K, const F& f, LAS unsigned char* lds, int bx, int G, int wave) {
;     ...
;     for (int t = bx; t < ntiles; t += G) {
;         const int rg = t % RG, n0 = (t / RG) * 16;
;         const int mt = rg * MTW + (wave % MTW), kq = wave / MTW;
;         const bf16_t* ap = A + (size_t)(MP + 16 * mt + fr) * K + kq * klen + 8 * fq;
;         const bf16_t* bp = Bt + (size_t)(n0 + fr) * K + kq * klen + 8 * fq;
;         f32x4 acc = (f32x4){0.f, 0.f, 0.f, 0.f};
; #pragma unroll 16
;         for (int k = 0; k < klen; k += 32) {
;             const bf16x8 af = *(const bf16x8*)(ap + k), bf = *(const bf16x8*)(bp + k);
;             acc = __builtin_amdgcn_mfma_f32_16x16x32_bf16(bf, af, acc, 0, 0, 0);
;         }
;         if (KSPLIT > 1) {
;             __syncthreads();
;             *(LAS f32x4*)(lds + wave * 1024 + lane * 16) = acc;
;             __syncthreads();
;             if (kq == 0) {
.LBB0_2227:
	s_ashr_i32 s0, s4, 31
	s_lshr_b32 s0, s0, 30
	s_add_i32 s0, s4, s0
	s_ashr_i32 s8, s0, 2
	s_lshl_b32 s1, s8, 7
	v_subrev_u32_e32 v12, s1, v23
	v_add_u32_e32 v4, 0x4000, v12
	v_mov_b32_e32 v5, v2
	s_lshl_b32 s0, s8, 4
	v_lshlrev_b64 v[4:5], 11, v[4:5]
	v_lshl_add_u64 v[26:27], v[0:1], 0, v[4:5]
	v_or_b32_e32 v4, s0, v3
	v_ashrrev_i32_e32 v5, 31, v4
	v_lshlrev_b64 v[4:5], 11, v[4:5]
	v_lshl_add_u64 v[28:29], v[8:9], 0, v[4:5]
	s_waitcnt lgkmcnt(0)
	v_readlane_b32 s10, v253, 39
	v_readlane_b32 s11, v253, 40
	s_andn2_b64 vcc, exec, s[10:11]
	v_readlane_b32 s100, v251, 60
	s_mul_i32 s100, s100, 0x3000
	s_add_i32 s100, s100, 0x2000
	v_lshrrev_b32_e32 v202, 2, v219
	v_and_b32_e32 v203, 15, v219
	v_lshrrev_b32_e32 v201, 4, v219
	v_sub_u32_e32 v202, v202, v203
	v_lshlrev_b32_e32 v202, 11, v202
	v_and_b32_e32 v204, 3, v219
	v_xor_b32_e32 v204, v204, v201
	v_sub_u32_e32 v204, v204, v201
	v_lshl_add_u32 v202, v204, 4, v202
	v_lshrrev_b32_e32 v204, 2, v203
	v_xor_b32_e32 v204, v204, v201
	v_lshlrev_b32_e32 v200, 6, v203
	v_lshl_add_u32 v200, v204, 4, v200
	v_add_u32_e32 v200, s100, v200
	v_ashrrev_i32_e32 v203, 31, v202
	v_lshl_add_u64 v[196:197], v[202:203], 0, v[26:27]
	v_lshl_add_u64 v[198:199], v[202:203], 0, v[28:29]
	s_add_i32 m0, s100, 0
	s_nop 0
	global_load_lds_dwordx4 v[196:197], off
	s_add_i32 m0, s100, 1024
	s_nop 0
	global_load_lds_dwordx4 v[198:199], off
	s_add_i32 m0, s100, 1984
	s_nop 0
	global_load_lds_dwordx4 v[196:197], off offset:64
	s_add_i32 m0, s100, 3008
	s_nop 0
	global_load_lds_dwordx4 v[198:199], off offset:64
	s_add_i32 m0, s100, 3968
	s_nop 0
	global_load_lds_dwordx4 v[196:197], off offset:128
	s_add_i32 m0, s100, 4992
	s_nop 0
	global_load_lds_dwordx4 v[198:199], off offset:128
	s_add_i32 m0, s100, 5952
	s_nop 0
	global_load_lds_dwordx4 v[196:197], off offset:192
	s_add_i32 m0, s100, 6976
	s_nop 0
	global_load_lds_dwordx4 v[198:199], off offset:192
	s_add_i32 m0, s100, 7936
	s_nop 0
	global_load_lds_dwordx4 v[196:197], off offset:256
	s_add_i32 m0, s100, 8960
	s_nop 0
	global_load_lds_dwordx4 v[198:199], off offset:256
	s_add_i32 m0, s100, 9920
	s_nop 0
	global_load_lds_dwordx4 v[196:197], off offset:320
	s_add_i32 m0, s100, 10944
	s_nop 0
	global_load_lds_dwordx4 v[198:199], off offset:320
	s_waitcnt vmcnt(10)
	ds_read_b128 v[180:183], v200 offset:0
	ds_read_b128 v[184:187], v200 offset:1024
	s_waitcnt vmcnt(8)
	ds_read_b128 v[188:191], v200 offset:2048
	ds_read_b128 v[192:195], v200 offset:3072
	s_waitcnt lgkmcnt(2)
	v_mfma_f32_16x16x32_bf16 v[4:7], v[184:187], v[180:183], 0
	s_add_i32 m0, s100, -384
	s_nop 0
	global_load_lds_dwordx4 v[196:197], off offset:384
	s_add_i32 m0, s100, 640
	s_nop 0
	global_load_lds_dwordx4 v[198:199], off offset:384
	s_waitcnt vmcnt(8)
	ds_read_b128 v[180:183], v200 offset:4096
	ds_read_b128 v[184:187], v200 offset:5120
	s_waitcnt lgkmcnt(2)
	v_mfma_f32_16x16x32_bf16 v[4:7], v[192:195], v[188:191], v[4:7]
	s_add_i32 m0, s100, 1600
	s_nop 0
	global_load_lds_dwordx4 v[196:197], off offset:448
	s_add_i32 m0, s100, 2624
	s_nop 0
	global_load_lds_dwordx4 v[198:199], off offset:448
	s_waitcnt vmcnt(8)
	ds_read_b128 v[188:191], v200 offset:6144
	ds_read_b128 v[192:195], v200 offset:7168
	s_waitcnt lgkmcnt(2)
	v_mfma_f32_16x16x32_bf16 v[4:7], v[184:187], v[180:183], v[4:7]
	s_waitcnt vmcnt(6)
	ds_read_b128 v[180:183], v200 offset:8192
	ds_read_b128 v[184:187], v200 offset:9216
	s_waitcnt lgkmcnt(2)
	v_mfma_f32_16x16x32_bf16 v[4:7], v[192:195], v[188:191], v[4:7]
	s_waitcnt vmcnt(4)
	ds_read_b128 v[188:191], v200 offset:10240
	ds_read_b128 v[192:195], v200 offset:11264
	s_waitcnt lgkmcnt(2)
	v_mfma_f32_16x16x32_bf16 v[4:7], v[184:187], v[180:183], v[4:7]
	s_waitcnt vmcnt(2)
	ds_read_b128 v[180:183], v200 offset:0
	ds_read_b128 v[184:187], v200 offset:1024
	s_waitcnt lgkmcnt(2)
	v_mfma_f32_16x16x32_bf16 v[4:7], v[192:195], v[188:191], v[4:7]
	s_waitcnt vmcnt(0)
	ds_read_b128 v[188:191], v200 offset:2048
	ds_read_b128 v[192:195], v200 offset:3072
	s_waitcnt lgkmcnt(2)
	v_mfma_f32_16x16x32_bf16 v[4:7], v[184:187], v[180:183], v[4:7]
	s_waitcnt lgkmcnt(0)
	s_barrier
	v_mfma_f32_16x16x32_bf16 v[4:7], v[192:195], v[188:191], v[4:7]
	s_nop 7
	ds_write_b128 v25, v[4:7]
	s_waitcnt lgkmcnt(0)
	s_barrier
	s_cbranch_vccnz .LBB0_2226
; __device__ __forceinline__ u32x2 pk4(f32x4 v) { u32x2 r; r.x = pk2(v.x, v.y); r.y = pk2(v.z, v.w); return r; }
; __device__ __forceinline__ void stats_sk(const float* sts, int row, int fq, float& mu, float& rs) {
;     const f32x4* p = (const f32x4*)(sts + (size_t)(row - MP) * 128 + fq * 32);
;     float s1 = 0.f, s2 = 0.f;
; #pragma unroll
;     for (int i = 0; i < 8; ++i) { const f32x4 a = p[i]; s1 += a.x + a.z; s2 += a.y + a.w; }
;     s1 += __shfl_xor(s1, 16); s2 += __shfl_xor(s2, 16); s1 += __shfl_xor(s1, 32); s2 += __shfl_xor(s2, 32);
;     mu = s1 * (1.f / DM); rs = __builtin_amdgcn_rsqf(fmaxf(s2 * (1.f / DM) - mu * mu, 0.f) + LN_EPS);
;     __device__ __forceinline__ void sk(int row, int col, f32x4 v, int fq) const {
;         float mu = 0.f, rs = 1.f; if (ln) stats_sk(sts_p, row, fq, mu, rs);
;         const u32x2 raw = *(const u32x2*)(src + (size_t)row * DM + col);
;         f32x4 x = (f32x4){bflo(raw.x), bfhi(raw.x), bflo(raw.y), bfhi(raw.y)};
;         if (ln) x = (x - mu) * rs * *(const f32x4*)(g + col) + *(const f32x4*)(b + col);
;         const u32x2 pz = pk4(x * ALPHA + v);
;         *(u32x2*)(dst + (size_t)row * DM + col) = pz;
;         const float z0 = bflo(pz.x), z1 = bfhi(pz.x), z2 = bflo(pz.y), z3 = bfhi(pz.y);
;         float s1 = (z0 + z1) + (z2 + z3), s2 = (z0 * z0 + z1 * z1) + (z2 * z2 + z3 * z3);
;         s1 += __shfl_xor(s1, 16); s2 += __shfl_xor(s2, 16); s1 += __shfl_xor(s1, 32); s2 += __shfl_xor(s2, 32);
;         if (fq == 0) { float* p = sts_n + (size_t)(row - MP) * 128 + (col >> 4) * 2; p[0] = s1; p[1] = s2; }
	ds_read_b128 v[14:17], v25 offset:2048
	v_ashrrev_i32_e32 v13, 31, v12
	v_lshlrev_b64 v[12:13], 9, v[12:13]
	v_lshl_add_u64 v[20:21], v[10:11], 0, v[12:13]
	s_waitcnt lgkmcnt(0)
	v_pk_add_f32 v[16:17], v[6:7], v[16:17]
	v_pk_add_f32 v[14:15], v[4:5], v[14:15]
	ds_read_b128 v[4:7], v25 offset:4096
	s_waitcnt lgkmcnt(0)
	v_pk_add_f32 v[6:7], v[16:17], v[6:7]
	v_pk_add_f32 v[18:19], v[14:15], v[4:5]
	ds_read_b128 v[14:17], v25 offset:6144
	s_waitcnt lgkmcnt(0)
	v_pk_add_f32 v[4:5], v[6:7], v[16:17]
	v_pk_add_f32 v[6:7], v[18:19], v[14:15]
	global_load_dwordx4 v[16:19], v[20:21], off offset:48
	global_load_dwordx4 v[28:31], v[20:21], off offset:32
	global_load_dwordx4 v[32:35], v[20:21], off offset:16
	global_load_dwordx4 v[36:39], v[20:21], off
	global_load_dwordx4 v[40:43], v[20:21], off offset:112
	global_load_dwordx4 v[44:47], v[20:21], off offset:96
	global_load_dwordx4 v[48:51], v[20:21], off offset:80
	global_load_dwordx4 v[52:55], v[20:21], off offset:64
	v_add_u32_e32 v192, s0, v22
	s_lshl_b32 s101, s8, 17
	v_subrev_u32_e32 v180, s101, v24
	v_mov_b32_e32 v181, v2
	v_lshl_add_u64 v[180:181], v[180:181], 1, s[70:71]
	v_ashrrev_i32_e32 v193, 31, v192
	v_lshl_add_u64 v[180:181], v[192:193], 1, v[180:181]
	global_load_dwordx2 v[182:183], v[180:181], off
	v_lshlrev_b64 v[192:193], 2, v[192:193]
	v_lshl_add_u64 v[184:185], s[46:47], 0, v[192:193]
	v_lshl_add_u64 v[188:189], s[48:49], 0, v[192:193]
	global_load_dwordx4 v[184:187], v[184:185], off
	s_nop 0
	global_load_dwordx4 v[188:191], v[188:189], off
	v_and_b32_e32 v20, 64, v219
	v_xor_b32_e32 v15, 16, v219
	v_add_u32_e32 v20, 64, v20
	v_cmp_lt_i32_e32 vcc, v15, v20
	v_add_u32_e32 v14, s0, v22
	s_lshl_b32 s0, s8, 17
	v_cndmask_b32_e32 v15, v219, v15, vcc
	v_lshlrev_b32_e32 v27, 2, v15
	v_xor_b32_e32 v15, 32, v219
	v_cmp_lt_i32_e32 vcc, v15, v20
	s_waitcnt vmcnt(10)
	v_pk_add_f32 v[16:17], v[16:17], v[18:19]
	s_waitcnt vmcnt(9)
	v_pk_add_f32 v[28:29], v[28:29], v[30:31]
	s_waitcnt vmcnt(8)
	v_pk_add_f32 v[32:33], v[32:33], v[34:35]
	s_waitcnt vmcnt(7)
	v_pk_add_f32 v[20:21], v[36:37], v[38:39]
	v_cndmask_b32_e32 v15, v219, v15, vcc
	v_pk_add_f32 v[20:21], v[20:21], 0 op_sel_hi:[1,0]
	v_lshlrev_b32_e32 v26, 2, v15
	v_pk_add_f32 v[20:21], v[20:21], v[32:33]
	s_waitcnt vmcnt(3)
	v_pk_add_f32 v[18:19], v[52:53], v[54:55]
	v_pk_add_f32 v[20:21], v[20:21], v[28:29]
	s_nop 0
	v_pk_add_f32 v[16:17], v[20:21], v[16:17]
	s_nop 0
	v_pk_add_f32 v[16:17], v[16:17], v[18:19]
	v_pk_add_f32 v[18:19], v[48:49], v[50:51]
	s_nop 0
	v_pk_add_f32 v[16:17], v[16:17], v[18:19]
	v_pk_add_f32 v[18:19], v[44:45], v[46:47]
	s_nop 0
	v_pk_add_f32 v[16:17], v[16:17], v[18:19]
	v_pk_add_f32 v[18:19], v[40:41], v[42:43]
	s_nop 0
	v_pk_add_f32 v[16:17], v[16:17], v[18:19]
	ds_bpermute_b32 v18, v27, v16
	ds_bpermute_b32 v19, v27, v17
	s_waitcnt lgkmcnt(0)
	v_pk_add_f32 v[16:17], v[16:17], v[18:19]
	ds_bpermute_b32 v18, v26, v16
	ds_bpermute_b32 v19, v26, v17
	s_waitcnt lgkmcnt(0)
	v_pk_add_f32 v[16:17], v[16:17], v[18:19]
	s_nop 0
	v_pk_mul_f32 v[18:19], v[16:17], s[82:83] op_sel_hi:[1,0]
	v_subrev_u32_e32 v16, s0, v24
	v_fma_f32 v15, -v18, v18, v19
	v_max_f32_e32 v15, 0, v15
	v_add_f32_e32 v15, 0x3727c5ac, v15
	v_mov_b32_e32 v17, v2
	v_rsq_f32_e32 v20, v15
	v_lshl_add_u64 v[16:17], v[16:17], 1, s[70:71]
	v_ashrrev_i32_e32 v15, 31, v14
	v_lshl_add_u64 v[16:17], v[14:15], 1, v[16:17]
	s_waitcnt vmcnt(2)
	v_mov_b32_e32 v28, v182
	v_mov_b32_e32 v29, v183
	v_lshlrev_b64 v[14:15], 2, v[14:15]
	s_nop 0
	v_lshlrev_b32_e32 v19, 16, v28
	v_and_b32_e32 v21, 0xffff0000, v28
	v_lshlrev_b32_e32 v30, 16, v29
	v_and_b32_e32 v31, 0xffff0000, v29
	v_sub_f32_e32 v29, v21, v18
	v_sub_f32_e32 v28, v19, v18
	v_sub_f32_e32 v19, v31, v18
	v_sub_f32_e32 v18, v30, v18
	v_pk_mul_f32 v[18:19], v[20:21], v[18:19] op_sel_hi:[0,1]
	v_pk_mul_f32 v[20:21], v[20:21], v[28:29] op_sel_hi:[0,1]
	v_lshl_add_u64 v[28:29], s[46:47], 0, v[14:15]
	v_lshl_add_u64 v[14:15], s[48:49], 0, v[14:15]
	s_waitcnt vmcnt(0)
	v_mov_b32_e32 v28, v184
	v_mov_b32_e32 v29, v185
	v_mov_b32_e32 v30, v186
	v_mov_b32_e32 v31, v187
	s_nop 0
	v_mov_b32_e32 v32, v188
	v_mov_b32_e32 v33, v189
	v_mov_b32_e32 v34, v190
	v_mov_b32_e32 v35, v191
	s_waitcnt vmcnt(0)
	v_pk_fma_f32 v[14:15], v[28:29], v[20:21], v[32:33]
	v_pk_fma_f32 v[18:19], v[30:31], v[18:19], v[34:35]
	v_pk_fma_f32 v[6:7], v[14:15], s[72:73], v[6:7] op_sel_hi:[1,0,1]
	v_pk_fma_f32 v[4:5], v[18:19], s[72:73], v[4:5] op_sel_hi:[1,0,1]
	v_cvt_pk_bf16_f32 v6, v6, v7
	v_cvt_pk_bf16_f32 v7, v4, v5
	global_store_dwordx2 v[16:17], v[6:7], off
	v_lshlrev_b32_e32 v4, 16, v6
	v_and_b32_e32 v6, 0xffff0000, v6
	v_lshlrev_b32_e32 v14, 16, v7
	v_and_b32_e32 v16, 0xffff0000, v7
	v_mul_f32_e32 v5, v4, v4
	v_mul_f32_e32 v7, v6, v6
	v_mul_f32_e32 v15, v14, v14
	v_mul_f32_e32 v17, v16, v16
	v_pk_add_f32 v[4:5], v[4:5], v[6:7]
	v_pk_add_f32 v[6:7], v[14:15], v[16:17]
	s_nop 0
	v_pk_add_f32 v[4:5], v[4:5], v[6:7]
	ds_bpermute_b32 v6, v27, v4
	ds_bpermute_b32 v7, v27, v5
	s_waitcnt lgkmcnt(0)
	v_pk_add_f32 v[4:5], v[4:5], v[6:7]
	ds_bpermute_b32 v6, v26, v4
	ds_bpermute_b32 v7, v26, v5
	s_and_saveexec_b64 s[0:1], s[38:39]
	s_cbranch_execz .LBB0_2225
	s_lshl_b32 s8, s8, 1
	v_lshl_add_u64 v[12:13], s[40:41], 0, v[12:13]
	s_ashr_i32 s9, s8, 31
	v_lshl_add_u64 v[12:13], s[8:9], 2, v[12:13]
	s_waitcnt lgkmcnt(0)
	v_pk_add_f32 v[4:5], v[4:5], v[6:7]
	global_store_dwordx2 v[12:13], v[4:5], off
	s_branch .LBB0_2225

; template <int KSPLIT, class F>
; __device__ __forceinline__ void skinny_gemm(const bf16_t* A, const bf16_t* Bt, int N, int K, const F& f, LAS unsigned char* lds, int bx, int G, int wave) {
;     ...
;         const bf16_t* ap = A + (size_t)(MP + 16 * mt + fr) * K + kq * klen + 8 * fq;
;         const bf16_t* bp = Bt + (size_t)(n0 + fr) * K + kq * klen + 8 * fq;
;         f32x4 acc = (f32x4){0.f, 0.f, 0.f, 0.f};
; #pragma unroll 16
;         for (int k = 0; k < klen; k += 32) {
;             const bf16x8 af = *(const bf16x8*)(ap + k), bf = *(const bf16x8*)(bp + k);
;             acc = __builtin_amdgcn_mfma_f32_16x16x32_bf16(bf, af, acc, 0, 0, 0);
;         }
.LBB0_2402:
	v_readlane_b32 s100, v251, 60
	s_mul_i32 s100, s100, 0x3000
	s_add_i32 s100, s100, 0x2000
	v_lshrrev_b32_e32 v202, 2, v219
	v_and_b32_e32 v203, 15, v219
	v_lshrrev_b32_e32 v201, 4, v219
	v_sub_u32_e32 v202, v202, v203
	v_lshlrev_b32_e32 v202, 13, v202
	v_and_b32_e32 v204, 3, v219
	v_xor_b32_e32 v204, v204, v201
	v_sub_u32_e32 v204, v204, v201
	v_lshl_add_u32 v202, v204, 4, v202
	v_lshrrev_b32_e32 v204, 2, v203
	v_xor_b32_e32 v204, v204, v201
	v_lshlrev_b32_e32 v200, 6, v203
	v_lshl_add_u32 v200, v204, 4, v200
	v_add_u32_e32 v200, s100, v200
	v_ashrrev_i32_e32 v203, 31, v202
	v_lshl_add_u64 v[196:197], v[202:203], 0, v[16:17]
	v_lshl_add_u64 v[198:199], v[202:203], 0, v[14:15]
	s_add_i32 m0, s100, 512
	s_nop 0
	global_load_lds_dwordx4 v[196:197], off offset:-512
	s_add_i32 m0, s100, 1536
	s_nop 0
	global_load_lds_dwordx4 v[198:199], off offset:-512
	s_add_i32 m0, s100, 2496
	s_nop 0
	global_load_lds_dwordx4 v[196:197], off offset:-448
	s_add_i32 m0, s100, 3520
	s_nop 0
	global_load_lds_dwordx4 v[198:199], off offset:-448
	s_add_i32 m0, s100, 4480
	s_nop 0
	global_load_lds_dwordx4 v[196:197], off offset:-384
	s_add_i32 m0, s100, 5504
	s_nop 0
	global_load_lds_dwordx4 v[198:199], off offset:-384
	s_add_i32 m0, s100, 6464
	s_nop 0
	global_load_lds_dwordx4 v[196:197], off offset:-320
	s_add_i32 m0, s100, 7488
	s_nop 0
	global_load_lds_dwordx4 v[198:199], off offset:-320
	s_add_i32 m0, s100, 8448
	s_nop 0
	global_load_lds_dwordx4 v[196:197], off offset:-256
	s_add_i32 m0, s100, 9472
	s_nop 0
	global_load_lds_dwordx4 v[198:199], off offset:-256
	s_add_i32 m0, s100, 10432
	s_nop 0
	global_load_lds_dwordx4 v[196:197], off offset:-192
	s_add_i32 m0, s100, 11456
	s_nop 0
	global_load_lds_dwordx4 v[198:199], off offset:-192
	s_waitcnt vmcnt(10)
	ds_read_b128 v[180:183], v200 offset:0
	ds_read_b128 v[184:187], v200 offset:1024
	s_waitcnt vmcnt(8)
	ds_read_b128 v[188:191], v200 offset:2048
	ds_read_b128 v[192:195], v200 offset:3072
	s_waitcnt lgkmcnt(2)
	v_mfma_f32_16x16x32_bf16 v[4:7], v[184:187], v[180:183], v[4:7]
	s_add_i32 m0, s100, 128
	s_nop 0
	global_load_lds_dwordx4 v[196:197], off offset:-128
	s_add_i32 m0, s100, 1152
	s_nop 0
	global_load_lds_dwordx4 v[198:199], off offset:-128
	s_waitcnt vmcnt(8)
	ds_read_b128 v[180:183], v200 offset:4096
	ds_read_b128 v[184:187], v200 offset:5120
	s_waitcnt lgkmcnt(2)
	v_mfma_f32_16x16x32_bf16 v[4:7], v[192:195], v[188:191], v[4:7]
	s_add_i32 m0, s100, 2112
	s_nop 0
	global_load_lds_dwordx4 v[196:197], off offset:-64
	s_add_i32 m0, s100, 3136
	s_nop 0
	global_load_lds_dwordx4 v[198:199], off offset:-64
	s_waitcnt vmcnt(8)
	ds_read_b128 v[188:191], v200 offset:6144
	ds_read_b128 v[192:195], v200 offset:7168
	s_waitcnt lgkmcnt(2)
	v_mfma_f32_16x16x32_bf16 v[4:7], v[184:187], v[180:183], v[4:7]
	s_add_i32 m0, s100, 4096
	s_nop 0
	global_load_lds_dwordx4 v[196:197], off
	s_add_i32 m0, s100, 5120
	s_nop 0
	global_load_lds_dwordx4 v[198:199], off
	s_waitcnt vmcnt(8)
	ds_read_b128 v[180:183], v200 offset:8192
	ds_read_b128 v[184:187], v200 offset:9216
	s_waitcnt lgkmcnt(2)
	v_mfma_f32_16x16x32_bf16 v[4:7], v[192:195], v[188:191], v[4:7]
	s_add_i32 m0, s100, 6080
	s_nop 0
	global_load_lds_dwordx4 v[196:197], off offset:64
	s_add_i32 m0, s100, 7104
	s_nop 0
	global_load_lds_dwordx4 v[198:199], off offset:64
	s_waitcnt vmcnt(8)
	ds_read_b128 v[188:191], v200 offset:10240
	ds_read_b128 v[192:195], v200 offset:11264
	s_waitcnt lgkmcnt(2)
	v_mfma_f32_16x16x32_bf16 v[4:7], v[184:187], v[180:183], v[4:7]
	s_add_i32 m0, s100, 8064
	s_nop 0
	global_load_lds_dwordx4 v[196:197], off offset:128
	s_add_i32 m0, s100, 9088
	s_nop 0
	global_load_lds_dwordx4 v[198:199], off offset:128
	s_waitcnt vmcnt(8)
	ds_read_b128 v[180:183], v200 offset:0
	ds_read_b128 v[184:187], v200 offset:1024
	s_waitcnt lgkmcnt(2)
	v_mfma_f32_16x16x32_bf16 v[4:7], v[192:195], v[188:191], v[4:7]
	s_add_i32 m0, s100, 10048
	s_nop 0
	global_load_lds_dwordx4 v[196:197], off offset:192
	s_add_i32 m0, s100, 11072
	s_nop 0
	global_load_lds_dwordx4 v[198:199], off offset:192
	s_waitcnt vmcnt(8)
	ds_read_b128 v[188:191], v200 offset:2048
	ds_read_b128 v[192:195], v200 offset:3072
	s_waitcnt lgkmcnt(2)
	v_mfma_f32_16x16x32_bf16 v[4:7], v[184:187], v[180:183], v[4:7]
	s_add_i32 m0, s100, -256
	s_nop 0
	global_load_lds_dwordx4 v[196:197], off offset:256
	s_add_i32 m0, s100, 768
	s_nop 0
	global_load_lds_dwordx4 v[198:199], off offset:256
	s_waitcnt vmcnt(8)
	ds_read_b128 v[180:183], v200 offset:4096
	ds_read_b128 v[184:187], v200 offset:5120
	s_waitcnt lgkmcnt(2)
	v_mfma_f32_16x16x32_bf16 v[4:7], v[192:195], v[188:191], v[4:7]
	s_add_i32 m0, s100, 1728
	s_nop 0
	global_load_lds_dwordx4 v[196:197], off offset:320
	s_add_i32 m0, s100, 2752
	s_nop 0
	global_load_lds_dwordx4 v[198:199], off offset:320
	s_waitcnt vmcnt(8)
	ds_read_b128 v[188:191], v200 offset:6144
	ds_read_b128 v[192:195], v200 offset:7168
	s_waitcnt lgkmcnt(2)
	v_mfma_f32_16x16x32_bf16 v[4:7], v[184:187], v[180:183], v[4:7]
	s_add_i32 m0, s100, 3712
	s_nop 0
	global_load_lds_dwordx4 v[196:197], off offset:384
	s_add_i32 m0, s100, 4736
	s_nop 0
	global_load_lds_dwordx4 v[198:199], off offset:384
	s_waitcnt vmcnt(8)
	ds_read_b128 v[180:183], v200 offset:8192
	ds_read_b128 v[184:187], v200 offset:9216
	s_waitcnt lgkmcnt(2)
	v_mfma_f32_16x16x32_bf16 v[4:7], v[192:195], v[188:191], v[4:7]
	s_add_i32 m0, s100, 5696
	s_nop 0
	global_load_lds_dwordx4 v[196:197], off offset:448
	s_add_i32 m0, s100, 6720
	s_nop 0
	global_load_lds_dwordx4 v[198:199], off offset:448
	s_waitcnt vmcnt(8)
	ds_read_b128 v[188:191], v200 offset:10240
	ds_read_b128 v[192:195], v200 offset:11264
	s_waitcnt lgkmcnt(2)
; #define LAS __attribute__((address_space(3)))
; template <int KSPLIT, class F>
; __device__ __forceinline__ void skinny_gemm(const bf16_t* A, const bf16_t* Bt, int N, int K, const F& f, LAS unsigned char* lds, int bx, int G, int wave) {
;     ...
; #pragma unroll 16
;         for (int k = 0; k < klen; k += 32) {
;             const bf16x8 af = *(const bf16x8*)(ap + k), bf = *(const bf16x8*)(bp + k);
;             acc = __builtin_amdgcn_mfma_f32_16x16x32_bf16(bf, af, acc, 0, 0, 0);
;         }
;         if (KSPLIT > 1) {
;             __syncthreads();
;             *(LAS f32x4*)(lds + wave * 1024 + lane * 16) = acc;
;             __syncthreads();
	v_mfma_f32_16x16x32_bf16 v[4:7], v[184:187], v[180:183], v[4:7]
	s_add_i32 m0, s100, 7680
	s_nop 0
	global_load_lds_dwordx4 v[196:197], off offset:512
	s_add_i32 m0, s100, 8704
	s_nop 0
	global_load_lds_dwordx4 v[198:199], off offset:512
	s_waitcnt vmcnt(8)
	ds_read_b128 v[180:183], v200 offset:0
	ds_read_b128 v[184:187], v200 offset:1024
	s_waitcnt lgkmcnt(2)
	v_mfma_f32_16x16x32_bf16 v[4:7], v[192:195], v[188:191], v[4:7]
	s_add_i32 m0, s100, 9664
	s_nop 0
	global_load_lds_dwordx4 v[196:197], off offset:576
	s_add_i32 m0, s100, 10688
	s_nop 0
	global_load_lds_dwordx4 v[198:199], off offset:576
	s_waitcnt vmcnt(8)
	ds_read_b128 v[188:191], v200 offset:2048
	ds_read_b128 v[192:195], v200 offset:3072
	s_waitcnt lgkmcnt(2)
	v_mfma_f32_16x16x32_bf16 v[4:7], v[184:187], v[180:183], v[4:7]
	s_add_i32 m0, s100, -640
	s_nop 0
	global_load_lds_dwordx4 v[196:197], off offset:640
	s_add_i32 m0, s100, 384
	s_nop 0
	global_load_lds_dwordx4 v[198:199], off offset:640
	s_waitcnt vmcnt(8)
	ds_read_b128 v[180:183], v200 offset:4096
	ds_read_b128 v[184:187], v200 offset:5120
	s_waitcnt lgkmcnt(2)
	v_mfma_f32_16x16x32_bf16 v[4:7], v[192:195], v[188:191], v[4:7]
	s_add_i32 m0, s100, 1344
	s_nop 0
	global_load_lds_dwordx4 v[196:197], off offset:704
	s_add_i32 m0, s100, 2368
	s_nop 0
	global_load_lds_dwordx4 v[198:199], off offset:704
	s_waitcnt vmcnt(8)
	ds_read_b128 v[188:191], v200 offset:6144
	ds_read_b128 v[192:195], v200 offset:7168
	s_waitcnt lgkmcnt(2)
	v_mfma_f32_16x16x32_bf16 v[4:7], v[184:187], v[180:183], v[4:7]
	s_add_i32 m0, s100, 3328
	s_nop 0
	global_load_lds_dwordx4 v[196:197], off offset:768
	s_add_i32 m0, s100, 4352
	s_nop 0
	global_load_lds_dwordx4 v[198:199], off offset:768
	s_waitcnt vmcnt(8)
	ds_read_b128 v[180:183], v200 offset:8192
	ds_read_b128 v[184:187], v200 offset:9216
	s_waitcnt lgkmcnt(2)
	v_mfma_f32_16x16x32_bf16 v[4:7], v[192:195], v[188:191], v[4:7]
	s_add_i32 m0, s100, 5312
	s_nop 0
	global_load_lds_dwordx4 v[196:197], off offset:832
	s_add_i32 m0, s100, 6336
	s_nop 0
	global_load_lds_dwordx4 v[198:199], off offset:832
	s_waitcnt vmcnt(8)
	ds_read_b128 v[188:191], v200 offset:10240
	ds_read_b128 v[192:195], v200 offset:11264
	s_waitcnt lgkmcnt(2)
	v_mfma_f32_16x16x32_bf16 v[4:7], v[184:187], v[180:183], v[4:7]
	s_add_i32 m0, s100, 7296
	s_nop 0
	global_load_lds_dwordx4 v[196:197], off offset:896
	s_add_i32 m0, s100, 8320
	s_nop 0
	global_load_lds_dwordx4 v[198:199], off offset:896
	s_waitcnt vmcnt(8)
	ds_read_b128 v[180:183], v200 offset:0
	ds_read_b128 v[184:187], v200 offset:1024
	s_waitcnt lgkmcnt(2)
	v_mfma_f32_16x16x32_bf16 v[4:7], v[192:195], v[188:191], v[4:7]
	s_add_i32 m0, s100, 9280
	s_nop 0
	global_load_lds_dwordx4 v[196:197], off offset:960
	s_add_i32 m0, s100, 10304
	s_nop 0
	global_load_lds_dwordx4 v[198:199], off offset:960
	s_waitcnt vmcnt(8)
	ds_read_b128 v[188:191], v200 offset:2048
	ds_read_b128 v[192:195], v200 offset:3072
	s_waitcnt lgkmcnt(2)
	v_mfma_f32_16x16x32_bf16 v[4:7], v[184:187], v[180:183], v[4:7]
	s_add_i32 m0, s100, -1024
	s_nop 0
	global_load_lds_dwordx4 v[196:197], off offset:1024
	s_add_i32 m0, s100, 0
	s_nop 0
	global_load_lds_dwordx4 v[198:199], off offset:1024
	s_waitcnt vmcnt(8)
	ds_read_b128 v[180:183], v200 offset:4096
	ds_read_b128 v[184:187], v200 offset:5120
	s_waitcnt lgkmcnt(2)
	v_mfma_f32_16x16x32_bf16 v[4:7], v[192:195], v[188:191], v[4:7]
	s_add_i32 m0, s100, 960
	s_nop 0
	global_load_lds_dwordx4 v[196:197], off offset:1088
	s_add_i32 m0, s100, 1984
	s_nop 0
	global_load_lds_dwordx4 v[198:199], off offset:1088
	s_waitcnt vmcnt(8)
	ds_read_b128 v[188:191], v200 offset:6144
	ds_read_b128 v[192:195], v200 offset:7168
	s_waitcnt lgkmcnt(2)
	v_mfma_f32_16x16x32_bf16 v[4:7], v[184:187], v[180:183], v[4:7]
	s_add_i32 m0, s100, 2944
	s_nop 0
	global_load_lds_dwordx4 v[196:197], off offset:1152
	s_add_i32 m0, s100, 3968
	s_nop 0
	global_load_lds_dwordx4 v[198:199], off offset:1152
	s_waitcnt vmcnt(8)
	ds_read_b128 v[180:183], v200 offset:8192
	ds_read_b128 v[184:187], v200 offset:9216
	s_waitcnt lgkmcnt(2)
	v_mfma_f32_16x16x32_bf16 v[4:7], v[192:195], v[188:191], v[4:7]
	s_add_i32 m0, s100, 4928
	s_nop 0
	global_load_lds_dwordx4 v[196:197], off offset:1216
	s_add_i32 m0, s100, 5952
	s_nop 0
	global_load_lds_dwordx4 v[198:199], off offset:1216
	s_waitcnt vmcnt(8)
	ds_read_b128 v[188:191], v200 offset:10240
	ds_read_b128 v[192:195], v200 offset:11264
	s_waitcnt lgkmcnt(2)
	v_mfma_f32_16x16x32_bf16 v[4:7], v[184:187], v[180:183], v[4:7]
	s_add_i32 m0, s100, 6912
	s_nop 0
	global_load_lds_dwordx4 v[196:197], off offset:1280
	s_add_i32 m0, s100, 7936
	s_nop 0
	global_load_lds_dwordx4 v[198:199], off offset:1280
	s_waitcnt vmcnt(8)
	ds_read_b128 v[180:183], v200 offset:0
	ds_read_b128 v[184:187], v200 offset:1024
	s_waitcnt lgkmcnt(2)
	v_mfma_f32_16x16x32_bf16 v[4:7], v[192:195], v[188:191], v[4:7]
	s_add_i32 m0, s100, 8896
	s_nop 0
	global_load_lds_dwordx4 v[196:197], off offset:1344
	s_add_i32 m0, s100, 9920
	s_nop 0
	global_load_lds_dwordx4 v[198:199], off offset:1344
	s_waitcnt vmcnt(8)
	ds_read_b128 v[188:191], v200 offset:2048
	ds_read_b128 v[192:195], v200 offset:3072
	s_waitcnt lgkmcnt(2)
	v_mfma_f32_16x16x32_bf16 v[4:7], v[184:187], v[180:183], v[4:7]
	s_add_i32 m0, s100, -1408
	s_nop 0
	global_load_lds_dwordx4 v[196:197], off offset:1408
	s_add_i32 m0, s100, -384
	s_nop 0
	global_load_lds_dwordx4 v[198:199], off offset:1408
	s_waitcnt vmcnt(8)
	ds_read_b128 v[180:183], v200 offset:4096
	ds_read_b128 v[184:187], v200 offset:5120
	s_waitcnt lgkmcnt(2)
	v_mfma_f32_16x16x32_bf16 v[4:7], v[192:195], v[188:191], v[4:7]
	s_add_i32 m0, s100, 576
	s_nop 0
	global_load_lds_dwordx4 v[196:197], off offset:1472
	s_add_i32 m0, s100, 1600
	s_nop 0
	global_load_lds_dwordx4 v[198:199], off offset:1472
	s_waitcnt vmcnt(8)
	ds_read_b128 v[188:191], v200 offset:6144
	ds_read_b128 v[192:195], v200 offset:7168
	s_waitcnt lgkmcnt(2)
	v_mfma_f32_16x16x32_bf16 v[4:7], v[184:187], v[180:183], v[4:7]
	s_waitcnt vmcnt(6)
	ds_read_b128 v[180:183], v200 offset:8192
	ds_read_b128 v[184:187], v200 offset:9216
	s_waitcnt lgkmcnt(2)
	v_mfma_f32_16x16x32_bf16 v[4:7], v[192:195], v[188:191], v[4:7]
	s_waitcnt vmcnt(4)
	ds_read_b128 v[188:191], v200 offset:10240
	ds_read_b128 v[192:195], v200 offset:11264
	s_waitcnt lgkmcnt(2)
	v_mfma_f32_16x16x32_bf16 v[4:7], v[184:187], v[180:183], v[4:7]
	s_waitcnt vmcnt(2)
	ds_read_b128 v[180:183], v200 offset:0
	ds_read_b128 v[184:187], v200 offset:1024
	s_waitcnt lgkmcnt(2)
	v_mfma_f32_16x16x32_bf16 v[4:7], v[192:195], v[188:191], v[4:7]
	s_waitcnt vmcnt(0)
	ds_read_b128 v[188:191], v200 offset:2048
	ds_read_b128 v[192:195], v200 offset:3072
	s_waitcnt lgkmcnt(2)
	v_mfma_f32_16x16x32_bf16 v[4:7], v[184:187], v[180:183], v[4:7]
	s_waitcnt lgkmcnt(0)
	v_mfma_f32_16x16x32_bf16 v[4:7], v[192:195], v[188:191], v[4:7]
	s_nop 0
	v_readlane_b32 s8, v253, 39
	v_readlane_b32 s9, v253, 40
	s_andn2_b64 vcc, exec, s[8:9]
	s_barrier
; __device__ __forceinline__ u32x2 pk4(f32x4 v) { u32x2 r; r.x = pk2(v.x, v.y); r.y = pk2(v.z, v.w); return r; }
; __device__ __forceinline__ void stats_sk(const float* sts, int row, int fq, float& mu, float& rs) {
;     const f32x4* p = (const f32x4*)(sts + (size_t)(row - MP) * 128 + fq * 32);
;     float s1 = 0.f, s2 = 0.f;
; #pragma unroll
;     for (int i = 0; i < 8; ++i) { const f32x4 a = p[i]; s1 += a.x + a.z; s2 += a.y + a.w; }
;     s1 += __shfl_xor(s1, 16); s2 += __shfl_xor(s2, 16); s1 += __shfl_xor(s1, 32); s2 += __shfl_xor(s2, 32);
;     mu = s1 * (1.f / DM); rs = __builtin_amdgcn_rsqf(fmaxf(s2 * (1.f / DM) - mu * mu, 0.f) + LN_EPS);
;     __device__ __forceinline__ void sk(int row, int col, f32x4 v, int fq) const {
;         float mu = 0.f, rs = 1.f; if (ln) stats_sk(sts_p, row, fq, mu, rs);
;         const u32x2 raw = *(const u32x2*)(src + (size_t)row * DM + col);
;         f32x4 x = (f32x4){bflo(raw.x), bfhi(raw.x), bflo(raw.y), bfhi(raw.y)};
;         if (ln) x = (x - mu) * rs * *(const f32x4*)(g + col) + *(const f32x4*)(b + col);
;         const u32x2 pz = pk4(x * ALPHA + v);
;         *(u32x2*)(dst + (size_t)row * DM + col) = pz;
;         const float z0 = bflo(pz.x), z1 = bfhi(pz.x), z2 = bflo(pz.y), z3 = bfhi(pz.y);
;         float s1 = (z0 + z1) + (z2 + z3), s2 = (z0 * z0 + z1 * z1) + (z2 * z2 + z3 * z3);
;         s1 += __shfl_xor(s1, 16); s2 += __shfl_xor(s2, 16); s1 += __shfl_xor(s1, 32); s2 += __shfl_xor(s2, 32);
;         if (fq == 0) { float* p = sts_n + (size_t)(row - MP) * 128 + (col >> 4) * 2; p[0] = s1; p[1] = s2; }
	s_nop 2
	ds_write_b128 v24, v[4:7]
	s_waitcnt lgkmcnt(0)
	s_barrier
	s_cbranch_vccnz .LBB0_2400
	ds_read_b128 v[14:17], v24 offset:2048
	v_ashrrev_i32_e32 v13, 31, v12
	s_waitcnt lgkmcnt(0)
	v_pk_add_f32 v[16:17], v[6:7], v[16:17]
	v_pk_add_f32 v[14:15], v[4:5], v[14:15]
	ds_read_b128 v[4:7], v24 offset:4096
	s_waitcnt lgkmcnt(0)
	v_pk_add_f32 v[6:7], v[16:17], v[6:7]
	v_pk_add_f32 v[18:19], v[14:15], v[4:5]
	ds_read_b128 v[14:17], v24 offset:6144
	s_waitcnt lgkmcnt(0)
	v_pk_add_f32 v[4:5], v[6:7], v[16:17]
	v_add_u32_e32 v16, s0, v23
	s_mov_b32 s0, 0xff800000
	v_pk_add_f32 v[6:7], v[18:19], v[14:15]
	v_lshlrev_b64 v[14:15], 9, v[12:13]
	s_mov_b32 s1, -1
	v_lshl_add_u64 v[14:15], v[14:15], 0, s[0:1]
	v_lshl_add_u64 v[26:27], v[0:1], 0, v[14:15]
	global_load_dwordx4 v[18:21], v[26:27], off offset:48
	global_load_dwordx4 v[28:31], v[26:27], off offset:32
	global_load_dwordx4 v[32:35], v[26:27], off offset:16
	global_load_dwordx4 v[36:39], v[26:27], off
	global_load_dwordx4 v[40:43], v[26:27], off offset:112
	global_load_dwordx4 v[44:47], v[26:27], off offset:96
	global_load_dwordx4 v[48:51], v[26:27], off offset:80
	global_load_dwordx4 v[52:55], v[26:27], off offset:64
	v_lshlrev_b32_e32 v180, 11, v12
	v_mov_b32_e32 v181, v2
	v_lshl_add_u64 v[180:181], s[70:71], 0, v[180:181]
	v_mov_b32_e32 v192, v16
	v_ashrrev_i32_e32 v193, 31, v16
	v_lshl_add_u64 v[180:181], v[192:193], 1, v[180:181]
	global_load_dwordx2 v[182:183], v[180:181], off
	v_lshlrev_b64 v[192:193], 2, v[192:193]
	v_lshl_add_u64 v[184:185], s[46:47], 0, v[192:193]
	v_lshl_add_u64 v[188:189], s[48:49], 0, v[192:193]
	global_load_dwordx4 v[184:187], v[184:185], off
	s_nop 0
	global_load_dwordx4 v[188:191], v[188:189], off
	v_and_b32_e32 v17, 64, v219
	v_xor_b32_e32 v13, 16, v219
	v_add_u32_e32 v17, 64, v17
	v_cmp_lt_i32_e32 vcc, v13, v17
	v_lshlrev_b32_e32 v12, 11, v12
	s_waitcnt vmcnt(10)
	v_pk_add_f32 v[18:19], v[18:19], v[20:21]
	s_waitcnt vmcnt(9)
	v_pk_add_f32 v[28:29], v[28:29], v[30:31]
	s_waitcnt vmcnt(8)
	v_pk_add_f32 v[32:33], v[32:33], v[34:35]
	s_waitcnt vmcnt(7)
	v_pk_add_f32 v[36:37], v[36:37], v[38:39]
	v_cndmask_b32_e32 v13, v219, v13, vcc
	v_pk_add_f32 v[36:37], v[36:37], 0 op_sel_hi:[1,0]
	v_lshlrev_b32_e32 v26, 2, v13
	v_pk_add_f32 v[32:33], v[36:37], v[32:33]
	s_waitcnt vmcnt(3)
	v_pk_add_f32 v[20:21], v[52:53], v[54:55]
	v_pk_add_f32 v[28:29], v[32:33], v[28:29]
	v_xor_b32_e32 v13, 32, v219
	v_pk_add_f32 v[18:19], v[28:29], v[18:19]
	v_cmp_lt_i32_e32 vcc, v13, v17
	v_pk_add_f32 v[18:19], v[18:19], v[20:21]
	v_pk_add_f32 v[20:21], v[48:49], v[50:51]
	v_cndmask_b32_e32 v13, v219, v13, vcc
	v_pk_add_f32 v[18:19], v[18:19], v[20:21]
	v_pk_add_f32 v[20:21], v[44:45], v[46:47]
	v_lshlrev_b32_e32 v25, 2, v13
	v_pk_add_f32 v[18:19], v[18:19], v[20:21]
	v_pk_add_f32 v[20:21], v[40:41], v[42:43]
	v_ashrrev_i32_e32 v17, 31, v16
	v_pk_add_f32 v[18:19], v[18:19], v[20:21]
	ds_bpermute_b32 v20, v26, v18
	ds_bpermute_b32 v21, v26, v19
	s_waitcnt lgkmcnt(0)
	v_pk_add_f32 v[18:19], v[18:19], v[20:21]
	ds_bpermute_b32 v20, v25, v18
	ds_bpermute_b32 v21, v25, v19
	s_waitcnt lgkmcnt(0)
	v_pk_add_f32 v[18:19], v[18:19], v[20:21]
	s_nop 0
	v_pk_mul_f32 v[18:19], v[18:19], s[82:83] op_sel_hi:[1,0]
	s_nop 0
	v_fma_f32 v13, -v18, v18, v19
	v_max_f32_e32 v13, 0, v13
	v_add_f32_e32 v13, 0x3727c5ac, v13
	v_rsq_f32_e32 v20, v13
	v_mov_b32_e32 v13, v2
	v_lshl_add_u64 v[12:13], s[70:71], 0, v[12:13]
	v_lshl_add_u64 v[12:13], v[16:17], 1, v[12:13]
	s_waitcnt vmcnt(2)
	v_mov_b32_e32 v28, v182
	v_mov_b32_e32 v29, v183
	v_lshlrev_b64 v[16:17], 2, v[16:17]
	s_nop 0
	v_lshlrev_b32_e32 v19, 16, v28
	v_and_b32_e32 v21, 0xffff0000, v28
	v_lshlrev_b32_e32 v27, 16, v29
	v_and_b32_e32 v30, 0xffff0000, v29
	v_sub_f32_e32 v29, v21, v18
	v_sub_f32_e32 v28, v19, v18
	v_sub_f32_e32 v19, v30, v18
	v_sub_f32_e32 v18, v27, v18
	v_pk_mul_f32 v[18:19], v[20:21], v[18:19] op_sel_hi:[0,1]
	v_pk_mul_f32 v[20:21], v[20:21], v[28:29] op_sel_hi:[0,1]
	v_lshl_add_u64 v[28:29], s[46:47], 0, v[16:17]
	v_lshl_add_u64 v[16:17], s[48:49], 0, v[16:17]
	s_waitcnt vmcnt(0)
	v_mov_b32_e32 v28, v184
	v_mov_b32_e32 v29, v185
	v_mov_b32_e32 v30, v186
	v_mov_b32_e32 v31, v187
	s_nop 0
	v_mov_b32_e32 v32, v188
	v_mov_b32_e32 v33, v189
	v_mov_b32_e32 v34, v190
	v_mov_b32_e32 v35, v191
	s_waitcnt vmcnt(0)
	v_pk_fma_f32 v[16:17], v[28:29], v[20:21], v[32:33]
	v_pk_fma_f32 v[18:19], v[30:31], v[18:19], v[34:35]
	v_pk_fma_f32 v[6:7], v[16:17], s[72:73], v[6:7] op_sel_hi:[1,0,1]
	v_pk_fma_f32 v[4:5], v[18:19], s[72:73], v[4:5] op_sel_hi:[1,0,1]
	v_cvt_pk_bf16_f32 v6, v6, v7
	v_cvt_pk_bf16_f32 v7, v4, v5
	global_store_dwordx2 v[12:13], v[6:7], off
	v_lshlrev_b32_e32 v4, 16, v6
	v_and_b32_e32 v6, 0xffff0000, v6
	v_lshlrev_b32_e32 v12, 16, v7
	v_and_b32_e32 v16, 0xffff0000, v7
	v_mul_f32_e32 v5, v4, v4
	v_mul_f32_e32 v7, v6, v6
	v_mul_f32_e32 v13, v12, v12
	v_mul_f32_e32 v17, v16, v16
	v_pk_add_f32 v[4:5], v[4:5], v[6:7]
	v_pk_add_f32 v[6:7], v[12:13], v[16:17]
	s_nop 0
	v_pk_add_f32 v[4:5], v[4:5], v[6:7]
	ds_bpermute_b32 v6, v26, v4
	ds_bpermute_b32 v7, v26, v5
	s_waitcnt lgkmcnt(0)
	v_pk_add_f32 v[4:5], v[4:5], v[6:7]
	ds_bpermute_b32 v6, v25, v4
	ds_bpermute_b32 v7, v25, v5
	s_and_saveexec_b64 s[0:1], s[36:37]
	s_cbranch_execz .LBB0_2399
	s_lshl_b32 s8, s4, 1
	v_lshl_add_u64 v[12:13], s[38:39], 0, v[14:15]
	s_ashr_i32 s9, s8, 31
	v_lshl_add_u64 v[12:13], s[8:9], 2, v[12:13]
	s_waitcnt lgkmcnt(0)
	v_pk_add_f32 v[4:5], v[4:5], v[6:7]
	global_store_dwordx2 v[12:13], v[4:5], off
	s_branch .LBB0_2399
